# f11 + P5 1/rms table precompute unrolled: all SS8 loads issued before the first wait
# baseline (speedup 1.0000x reference)
; #define LAS __attribute__((address_space(3)))
; __device__ __forceinline__ float frsq(float x) { return __builtin_amdgcn_rsqf(x); }
;     __device__ __forceinline__ bool next(int i, Unit& u) const { const int t = i / 3; const long L = (long)t * G + c; if (L >= tm.nwg) return false; tm.map((int)L, u.pm, u.pn); u.sub = i - 3 * t; return true; }
;     __device__ __forceinline__ bool next(int i, Unit& u) const { const long L = (long)i * G + c; if (L >= tm.nwg) return false; tm.map((int)L, u.pm, u.pn); u.pn += pn0; u.sub = i; return true; }
; __global__ void __launch_bounds__(NWAVES * 64, 2) mk_fwd(Args args) {
;     ...
;         { LAS float* rt = (LAS float*)(F.lds + RING_BYTES); const float* ss8 = WSP(float, WS_SS8);
;           for (int e = F.tid; e < 8 * BM_ROWS; e += NWAVES * 64) { const int ord = e >> 8, row = e & 255; pg8::Unit uu;
;               if (S.next(ord, uu)) { const float* p = ss8 + (size_t)(uu.pm * BM_ROWS + row) * 8; const f32x4 s0 = *(const f32x4*)p, s1 = *(const f32x4*)(p + 4);
;                   rt[e] = frsq((((s0[0] + s0[1]) + (s0[2] + s0[3])) + ((s1[0] + s1[1]) + (s1[2] + s1[3]))) * (1.0f / DM) + NORM_EPS); } }
;           __syncthreads(); }
.LBB0_1088:
	s_cmp_lt_i32 s60, 8
	s_cselect_b64 s[0:1], -1, 0
	s_cmp_gt_i32 s61, 7
	s_cselect_b64 s[4:5], -1, 0
	s_and_b64 s[0:1], s[0:1], s[4:5]
	s_andn2_b64 vcc, exec, s[0:1]
	s_cbranch_vccnz .LBB0_1182
	s_add_u32 s4, s34, 0x10a000
	s_addc_u32 s5, s35, 0
	s_ashr_i32 s3, s2, 31
	v_lshlrev_b32_e32 v10, 2, v0
	s_ashr_i32 s15, s14, 31
	v_lshrrev_b32_e32 v4, 8, v0
	s_waitcnt lgkmcnt(0)
	v_mov_b64_e32 v[2:3], s[2:3]
	v_add_u32_e32 v5, 0, v10
	v_and_b32_e32 v1, 0xff, v0
	v_mad_i64_i32 v[2:3], s[0:1], v4, s14, v[2:3]
	s_lshl_b64 s[8:9], s[14:15], 1
	v_or_b32_e32 v4, 0xfffffe00, v0
	v_add_u32_e32 v5, 0x20000, v5
	s_mov_b64 s[10:11], 0
	s_mov_b64 s[16:17], 0x580
	s_mov_b32 s12, 0x3e0f83e1
	s_movk_i32 s13, 0x84
	v_mov_b32_e32 v6, 0x358637bd
	s_movk_i32 s20, 0x5ff
	v_mov_b32_e32 v7, 0xb0
	v_mov_b32_e32 v8, 0xb1
	v_mov_b32_e32 v22, v2
	v_min_u32_e32 v22, 0x57f, v22
	v_ashrrev_i32_e32 v9, 31, v22
	v_lshrrev_b32_e32 v9, 29, v9
	v_add_u32_e32 v9, v22, v9
	v_ashrrev_i32_e32 v11, 3, v9
	v_and_b32_e32 v9, -8, v9
	v_sub_u32_e32 v9, v22, v9
	v_cmp_gt_i32_e64 s[0:1], 0, v9
	s_nop 1
	v_cndmask_b32_e64 v12, v7, v8, s[0:1]
	v_mul_lo_u32 v9, v9, v12
	v_add_u32_e32 v9, v9, v11
	v_mul_hi_i32 v11, v9, s12
	v_lshrrev_b32_e32 v12, 31, v11
	v_ashrrev_i32_e32 v11, 5, v11
	v_add_u32_e32 v11, v11, v12
	v_lshl_add_u32 v12, v11, 1, v11
	v_sub_u32_e32 v13, 32, v12
	v_min_i32_e32 v13, 3, v13
	v_sub_u32_e32 v14, 0, v13
	v_max_i32_e32 v13, v13, v14
	v_cvt_f32_u32_e32 v14, v13
	v_mul_lo_u32 v11, v11, s13
	v_sub_u32_e32 v9, v9, v11
	v_sub_u32_e32 v15, 0, v9
	v_rcp_iflag_f32_e32 v14, v14
	v_ashrrev_i32_e32 v11, 31, v9
	v_max_i32_e32 v9, v9, v15
	v_sub_u32_e32 v15, 0, v13
	v_mul_f32_e32 v14, 0x4f7ffffe, v14
	v_cvt_u32_f32_e32 v14, v14
	v_mul_lo_u32 v15, v15, v14
	v_mul_hi_u32 v15, v14, v15
	v_add_u32_e32 v14, v14, v15
	v_mul_hi_u32 v14, v9, v14
	v_mul_lo_u32 v14, v14, v13
	v_sub_u32_e32 v9, v9, v14
	v_sub_u32_e32 v14, v9, v13
	v_cmp_ge_u32_e64 s[0:1], v9, v13
	s_nop 1
	v_cndmask_b32_e64 v9, v9, v14, s[0:1]
	v_sub_u32_e32 v14, v9, v13
	v_cmp_ge_u32_e64 s[0:1], v9, v13
	s_nop 1
	v_cndmask_b32_e64 v9, v9, v14, s[0:1]
	v_xor_b32_e32 v9, v9, v11
	v_sub_u32_e32 v9, v9, v11
	v_add_u32_e32 v9, v12, v9
	v_lshl_or_b32 v12, v9, 8, v1
	v_ashrrev_i32_e32 v13, 31, v12
	v_lshlrev_b64 v[12:13], 5, v[12:13]
	v_lshl_add_u64 v[20:21], s[4:5], 0, v[12:13]
	global_load_dwordx4 v[100:103], v[20:21], off
	global_load_dwordx4 v[104:107], v[20:21], off offset:16
	v_add_u32_e32 v22, s8, v2
	v_min_u32_e32 v22, 0x57f, v22
	v_ashrrev_i32_e32 v9, 31, v22
	v_lshrrev_b32_e32 v9, 29, v9
	v_add_u32_e32 v9, v22, v9
	v_ashrrev_i32_e32 v11, 3, v9
	v_and_b32_e32 v9, -8, v9
	v_sub_u32_e32 v9, v22, v9
	v_cmp_gt_i32_e64 s[0:1], 0, v9
	s_nop 1
	v_cndmask_b32_e64 v12, v7, v8, s[0:1]
	v_mul_lo_u32 v9, v9, v12
	v_add_u32_e32 v9, v9, v11
	v_mul_hi_i32 v11, v9, s12
	v_lshrrev_b32_e32 v12, 31, v11
	v_ashrrev_i32_e32 v11, 5, v11
	v_add_u32_e32 v11, v11, v12
	v_lshl_add_u32 v12, v11, 1, v11
	v_sub_u32_e32 v13, 32, v12
	v_min_i32_e32 v13, 3, v13
	v_sub_u32_e32 v14, 0, v13
	v_max_i32_e32 v13, v13, v14
	v_cvt_f32_u32_e32 v14, v13
	v_mul_lo_u32 v11, v11, s13
	v_sub_u32_e32 v9, v9, v11
	v_sub_u32_e32 v15, 0, v9
	v_rcp_iflag_f32_e32 v14, v14
	v_ashrrev_i32_e32 v11, 31, v9
	v_max_i32_e32 v9, v9, v15
	v_sub_u32_e32 v15, 0, v13
	v_mul_f32_e32 v14, 0x4f7ffffe, v14
	v_cvt_u32_f32_e32 v14, v14
	v_mul_lo_u32 v15, v15, v14
	v_mul_hi_u32 v15, v14, v15
	v_add_u32_e32 v14, v14, v15
	v_mul_hi_u32 v14, v9, v14
	v_mul_lo_u32 v14, v14, v13
	v_sub_u32_e32 v9, v9, v14
	v_sub_u32_e32 v14, v9, v13
	v_cmp_ge_u32_e64 s[0:1], v9, v13
	s_nop 1
	v_cndmask_b32_e64 v9, v9, v14, s[0:1]
	v_sub_u32_e32 v14, v9, v13
	v_cmp_ge_u32_e64 s[0:1], v9, v13
	s_nop 1
	v_cndmask_b32_e64 v9, v9, v14, s[0:1]
	v_xor_b32_e32 v9, v9, v11
	v_sub_u32_e32 v9, v9, v11
	v_add_u32_e32 v9, v12, v9
	v_lshl_or_b32 v12, v9, 8, v1
	v_ashrrev_i32_e32 v13, 31, v12
	v_lshlrev_b64 v[12:13], 5, v[12:13]
	v_lshl_add_u64 v[20:21], s[4:5], 0, v[12:13]
	global_load_dwordx4 v[108:111], v[20:21], off
	global_load_dwordx4 v[112:115], v[20:21], off offset:16
	v_lshl_add_u32 v22, s8, 1, v2
	v_min_u32_e32 v22, 0x57f, v22
	v_ashrrev_i32_e32 v9, 31, v22
	v_lshrrev_b32_e32 v9, 29, v9
	v_add_u32_e32 v9, v22, v9
	v_ashrrev_i32_e32 v11, 3, v9
	v_and_b32_e32 v9, -8, v9
	v_sub_u32_e32 v9, v22, v9
	v_cmp_gt_i32_e64 s[0:1], 0, v9
; __device__ __forceinline__ float frsq(float x) { return __builtin_amdgcn_rsqf(x); }
;     __device__ __forceinline__ bool next(int i, Unit& u) const { const long L = (long)i * G + c; if (L >= tm.nwg) return false; tm.map((int)L, u.pm, u.pn); u.pn += pn0; u.sub = i; return true; }
;     __device__ __forceinline__ bool next(int i, Unit& u) const { const int t = i / 3; const long L = (long)t * G + c; if (L >= tm.nwg) return false; tm.map((int)L, u.pm, u.pn); u.sub = i - 3 * t; return true; }
; __global__ void __launch_bounds__(NWAVES * 64, 2) mk_fwd(Args args) {
;     ...
;           for (int e = F.tid; e < 8 * BM_ROWS; e += NWAVES * 64) { const int ord = e >> 8, row = e & 255; pg8::Unit uu;
;               if (S.next(ord, uu)) { const float* p = ss8 + (size_t)(uu.pm * BM_ROWS + row) * 8; const f32x4 s0 = *(const f32x4*)p, s1 = *(const f32x4*)(p + 4);
;                   rt[e] = frsq((((s0[0] + s0[1]) + (s0[2] + s0[3])) + ((s1[0] + s1[1]) + (s1[2] + s1[3]))) * (1.0f / DM) + NORM_EPS); } }
;           __syncthreads(); }
	s_nop 1
	v_cndmask_b32_e64 v12, v7, v8, s[0:1]
	v_mul_lo_u32 v9, v9, v12
	v_add_u32_e32 v9, v9, v11
	v_mul_hi_i32 v11, v9, s12
	v_lshrrev_b32_e32 v12, 31, v11
	v_ashrrev_i32_e32 v11, 5, v11
	v_add_u32_e32 v11, v11, v12
	v_lshl_add_u32 v12, v11, 1, v11
	v_sub_u32_e32 v13, 32, v12
	v_min_i32_e32 v13, 3, v13
	v_sub_u32_e32 v14, 0, v13
	v_max_i32_e32 v13, v13, v14
	v_cvt_f32_u32_e32 v14, v13
	v_mul_lo_u32 v11, v11, s13
	v_sub_u32_e32 v9, v9, v11
	v_sub_u32_e32 v15, 0, v9
	v_rcp_iflag_f32_e32 v14, v14
	v_ashrrev_i32_e32 v11, 31, v9
	v_max_i32_e32 v9, v9, v15
	v_sub_u32_e32 v15, 0, v13
	v_mul_f32_e32 v14, 0x4f7ffffe, v14
	v_cvt_u32_f32_e32 v14, v14
	v_mul_lo_u32 v15, v15, v14
	v_mul_hi_u32 v15, v14, v15
	v_add_u32_e32 v14, v14, v15
	v_mul_hi_u32 v14, v9, v14
	v_mul_lo_u32 v14, v14, v13
	v_sub_u32_e32 v9, v9, v14
	v_sub_u32_e32 v14, v9, v13
	v_cmp_ge_u32_e64 s[0:1], v9, v13
	s_nop 1
	v_cndmask_b32_e64 v9, v9, v14, s[0:1]
	v_sub_u32_e32 v14, v9, v13
	v_cmp_ge_u32_e64 s[0:1], v9, v13
	s_nop 1
	v_cndmask_b32_e64 v9, v9, v14, s[0:1]
	v_xor_b32_e32 v9, v9, v11
	v_sub_u32_e32 v9, v9, v11
	v_add_u32_e32 v9, v12, v9
	v_lshl_or_b32 v12, v9, 8, v1
	v_ashrrev_i32_e32 v13, 31, v12
	v_lshlrev_b64 v[12:13], 5, v[12:13]
	v_lshl_add_u64 v[20:21], s[4:5], 0, v[12:13]
	global_load_dwordx4 v[116:119], v[20:21], off
	global_load_dwordx4 v[120:123], v[20:21], off offset:16
	v_mad_u32_u24 v22, s8, 3, v2
	v_min_u32_e32 v22, 0x57f, v22
	v_ashrrev_i32_e32 v9, 31, v22
	v_lshrrev_b32_e32 v9, 29, v9
	v_add_u32_e32 v9, v22, v9
	v_ashrrev_i32_e32 v11, 3, v9
	v_and_b32_e32 v9, -8, v9
	v_sub_u32_e32 v9, v22, v9
	v_cmp_gt_i32_e64 s[0:1], 0, v9
	s_nop 1
	v_cndmask_b32_e64 v12, v7, v8, s[0:1]
	v_mul_lo_u32 v9, v9, v12
	v_add_u32_e32 v9, v9, v11
	v_mul_hi_i32 v11, v9, s12
	v_lshrrev_b32_e32 v12, 31, v11
	v_ashrrev_i32_e32 v11, 5, v11
	v_add_u32_e32 v11, v11, v12
	v_lshl_add_u32 v12, v11, 1, v11
	v_sub_u32_e32 v13, 32, v12
	v_min_i32_e32 v13, 3, v13
	v_sub_u32_e32 v14, 0, v13
	v_max_i32_e32 v13, v13, v14
	v_cvt_f32_u32_e32 v14, v13
	v_mul_lo_u32 v11, v11, s13
	v_sub_u32_e32 v9, v9, v11
	v_sub_u32_e32 v15, 0, v9
	v_rcp_iflag_f32_e32 v14, v14
	v_ashrrev_i32_e32 v11, 31, v9
	v_max_i32_e32 v9, v9, v15
	v_sub_u32_e32 v15, 0, v13
	v_mul_f32_e32 v14, 0x4f7ffffe, v14
	v_cvt_u32_f32_e32 v14, v14
	v_mul_lo_u32 v15, v15, v14
	v_mul_hi_u32 v15, v14, v15
	v_add_u32_e32 v14, v14, v15
	v_mul_hi_u32 v14, v9, v14
	v_mul_lo_u32 v14, v14, v13
	v_sub_u32_e32 v9, v9, v14
	v_sub_u32_e32 v14, v9, v13
	v_cmp_ge_u32_e64 s[0:1], v9, v13
	s_nop 1
	v_cndmask_b32_e64 v9, v9, v14, s[0:1]
	v_sub_u32_e32 v14, v9, v13
	v_cmp_ge_u32_e64 s[0:1], v9, v13
	s_nop 1
	v_cndmask_b32_e64 v9, v9, v14, s[0:1]
	v_xor_b32_e32 v9, v9, v11
	v_sub_u32_e32 v9, v9, v11
	v_add_u32_e32 v9, v12, v9
	v_lshl_or_b32 v12, v9, 8, v1
	v_ashrrev_i32_e32 v13, 31, v12
	v_lshlrev_b64 v[12:13], 5, v[12:13]
	v_lshl_add_u64 v[20:21], s[4:5], 0, v[12:13]
	global_load_dwordx4 v[124:127], v[20:21], off
	global_load_dwordx4 v[128:131], v[20:21], off offset:16
	s_waitcnt vmcnt(6)
	v_add_f32_e32 v12, v100, v101
	v_add_f32_e32 v13, v102, v103
	v_add_f32_e32 v14, v104, v105
	v_add_f32_e32 v15, v106, v107
	v_add_f32_e32 v12, v12, v13
	v_add_f32_e32 v14, v14, v15
	v_add_f32_e32 v11, v12, v14
	v_fmamk_f32 v11, v11, 0x3a000000, v6
	v_rsq_f32_e32 v11, v11
	s_nop 0
	ds_write_b32 v5, v11
	s_waitcnt vmcnt(4)
	v_add_f32_e32 v12, v108, v109
	v_add_f32_e32 v13, v110, v111
	v_add_f32_e32 v14, v112, v113
	v_add_f32_e32 v15, v114, v115
	v_add_f32_e32 v12, v12, v13
	v_add_f32_e32 v14, v14, v15
	v_add_f32_e32 v11, v12, v14
	v_fmamk_f32 v11, v11, 0x3a000000, v6
	v_rsq_f32_e32 v11, v11
	s_nop 0
	ds_write_b32 v5, v11 offset:2048
	s_waitcnt vmcnt(2)
	v_add_f32_e32 v12, v116, v117
	v_add_f32_e32 v13, v118, v119
	v_add_f32_e32 v14, v120, v121
	v_add_f32_e32 v15, v122, v123
	v_add_f32_e32 v12, v12, v13
	v_add_f32_e32 v14, v14, v15
	v_add_f32_e32 v11, v12, v14
	v_fmamk_f32 v11, v11, 0x3a000000, v6
	v_rsq_f32_e32 v11, v11
	s_nop 0
	ds_write_b32 v5, v11 offset:4096
	s_waitcnt vmcnt(0)
	v_add_f32_e32 v12, v124, v125
	v_add_f32_e32 v13, v126, v127
	v_add_f32_e32 v14, v128, v129
	v_add_f32_e32 v15, v130, v131
	v_add_f32_e32 v12, v12, v13
	v_add_f32_e32 v14, v14, v15
	v_add_f32_e32 v11, v12, v14
	v_fmamk_f32 v11, v11, 0x3a000000, v6
	v_rsq_f32_e32 v11, v11
	s_nop 0
	ds_write_b32 v5, v11 offset:6144
